# non-temporal hint on attention q-row loads and on P0's transposed-weight stores
# baseline (speedup 1.0000x reference)
.LBB0_169:
	v_add_u32_e32 v67, 0x420, v145
	v_add_u32_e32 v139, 0x428, v145
	v_add_u32_e32 v166, 0x840, v145
	v_add_u32_e32 v167, 0x848, v145
	v_add_u32_e32 v168, 0xc60, v145
	v_add_u32_e32 v169, 0xc68, v145
	v_add_u32_e32 v170, 0x1080, v145
	v_add_u32_e32 v171, 0x1088, v145
	v_add_u32_e32 v172, 0x14a0, v145
	v_add_u32_e32 v173, 0x14a8, v145
	v_add_u32_e32 v174, 0x18c0, v145
	v_add_u32_e32 v175, 0x18c8, v145
	v_add_u32_e32 v176, 0x1ce0, v145
	v_add_u32_e32 v177, 0x1ce8, v145
	s_waitcnt vmcnt(1)
	ds_write2_b32 v145, v6, v7 offset1:1
	ds_write2_b32 v145, v8, v9 offset0:2 offset1:3
	s_waitcnt vmcnt(0)
	ds_write2_b32 v67, v10, v11 offset1:1
	ds_write2_b32 v139, v12, v13 offset1:1
	ds_write2_b32 v166, v2, v3 offset1:1
	ds_write2_b32 v167, v4, v5 offset1:1
	ds_write2_b32 v168, v14, v15 offset1:1
	ds_write2_b32 v169, v16, v17 offset1:1
	ds_write2_b32 v170, v22, v23 offset1:1
	ds_write2_b32 v171, v24, v25 offset1:1
	ds_write2_b32 v172, v26, v27 offset1:1
	ds_write2_b32 v173, v28, v29 offset1:1
	ds_write2_b32 v174, v18, v19 offset1:1
	ds_write2_b32 v175, v20, v21 offset1:1
	ds_write2_b32 v176, v30, v31 offset1:1
	ds_write2_b32 v177, v32, v33 offset1:1
	s_waitcnt lgkmcnt(0)
	s_lshl_b32 s69, s82, 6
	ds_read2_b32 v[68:69], v137 offset0:33 offset1:41
	ds_read2_b32 v[150:151], v137 offset1:8
	ds_read2_b32 v[152:153], v137 offset0:66 offset1:74
	ds_read2_b32 v[154:155], v137 offset0:99 offset1:107
	ds_read2_b32 v[156:157], v137 offset0:132 offset1:140
	ds_read2_b32 v[158:159], v137 offset0:165 offset1:173
	ds_read2_b32 v[160:161], v137 offset0:198 offset1:206
	ds_read2_b32 v[162:163], v137 offset0:231 offset1:239
	s_add_i32 s69, s69, s85
	s_lshl_b32 s70, s83, 6
	s_waitcnt lgkmcnt(0)
	v_cvt_pk_bf16_f32 v146, v150, v68
	v_add_u32_e32 v68, s69, v1
	s_ashr_i32 s71, s70, 31
	v_mad_i64_i32 v[164:165], s[72:73], v68, s84, 0
	v_lshl_add_u64 v[164:165], v[164:165], 1, s[20:21]
	s_lshl_b64 s[70:71], s[70:71], 1
	v_lshl_add_u64 v[164:165], v[164:165], 0, s[70:71]
	v_mov_b32_e32 v141, v66
	v_cvt_pk_bf16_f32 v147, v152, v154
	v_cvt_pk_bf16_f32 v148, v156, v158
	v_cvt_pk_bf16_f32 v149, v160, v162
	v_lshl_add_u64 v[164:165], v[164:165], 0, v[140:141]
	v_add_u32_e32 v68, s69, v142
	global_store_dwordx4 v[164:165], v[146:149], off nt
	s_andn2_b64 vcc, exec, s[62:63]
	s_nop 0
	v_cvt_pk_bf16_f32 v146, v151, v69
	v_mad_i64_i32 v[68:69], s[72:73], v68, s84, 0
	v_lshl_add_u64 v[68:69], v[68:69], 1, s[20:21]
	v_lshl_add_u64 v[68:69], v[68:69], 0, s[70:71]
	v_cvt_pk_bf16_f32 v147, v153, v155
	v_cvt_pk_bf16_f32 v148, v157, v159
	v_cvt_pk_bf16_f32 v149, v161, v163
	v_lshl_add_u64 v[68:69], v[68:69], 0, v[140:141]
	ds_read2_b32 v[150:151], v137 offset0:16 offset1:24
	ds_read2_b32 v[152:153], v137 offset0:49 offset1:57
	ds_read2_b32 v[154:155], v137 offset0:82 offset1:90
	ds_read2_b32 v[156:157], v137 offset0:115 offset1:123
	ds_read2_b32 v[158:159], v137 offset0:148 offset1:156
	ds_read2_b32 v[160:161], v137 offset0:181 offset1:189
	ds_read2_b32 v[162:163], v137 offset0:214 offset1:222
	ds_read2_b32 v[164:165], v137 offset0:247 offset1:255
	global_store_dwordx4 v[68:69], v[146:149], off nt
	v_add_u32_e32 v68, s69, v143
	v_mad_i64_i32 v[68:69], s[72:73], v68, s84, 0
	v_lshl_add_u64 v[68:69], v[68:69], 1, s[20:21]
	v_lshl_add_u64 v[68:69], v[68:69], 0, s[70:71]
	s_waitcnt lgkmcnt(6)
	v_cvt_pk_bf16_f32 v146, v150, v152
	s_waitcnt lgkmcnt(4)
	v_cvt_pk_bf16_f32 v147, v154, v156
	s_waitcnt lgkmcnt(2)
	v_cvt_pk_bf16_f32 v148, v158, v160
	s_waitcnt lgkmcnt(0)
	v_cvt_pk_bf16_f32 v149, v162, v164
	v_lshl_add_u64 v[68:69], v[68:69], 0, v[140:141]
	global_store_dwordx4 v[68:69], v[146:149], off nt
	v_add_u32_e32 v68, s69, v144
	v_mad_i64_i32 v[68:69], s[72:73], v68, s84, 0
	v_lshl_add_u64 v[68:69], v[68:69], 1, s[20:21]
	v_lshl_add_u64 v[68:69], v[68:69], 0, s[70:71]
	v_cvt_pk_bf16_f32 v146, v151, v153
	v_cvt_pk_bf16_f32 v147, v155, v157
	v_cvt_pk_bf16_f32 v148, v159, v161
	v_cvt_pk_bf16_f32 v149, v163, v165
	v_lshl_add_u64 v[68:69], v[68:69], 0, v[140:141]
	global_store_dwordx4 v[68:69], v[146:149], off nt
	s_waitcnt lgkmcnt(0)
	ds_write2_b32 v145, v38, v39 offset1:1
	ds_write2_b32 v145, v40, v41 offset0:2 offset1:3
	ds_write2_b32 v67, v42, v43 offset1:1
	ds_write2_b32 v139, v44, v45 offset1:1
	ds_write2_b32 v166, v34, v35 offset1:1
	ds_write2_b32 v167, v36, v37 offset1:1
	ds_write2_b32 v168, v46, v47 offset1:1
	ds_write2_b32 v169, v48, v49 offset1:1
	ds_write2_b32 v170, v54, v55 offset1:1
	ds_write2_b32 v171, v56, v57 offset1:1
	ds_write2_b32 v172, v58, v59 offset1:1
	ds_write2_b32 v173, v60, v61 offset1:1
	ds_write2_b32 v174, v50, v51 offset1:1
	ds_write2_b32 v175, v52, v53 offset1:1
	ds_write2_b32 v176, v62, v63 offset1:1
	ds_write2_b32 v177, v64, v65 offset1:1
	s_waitcnt lgkmcnt(0)
	ds_read2_b32 v[68:69], v137 offset0:33 offset1:41
	ds_read2_b32 v[150:151], v137 offset1:8
	ds_read2_b32 v[152:153], v137 offset0:66 offset1:74
	ds_read2_b32 v[154:155], v137 offset0:99 offset1:107
	ds_read2_b32 v[156:157], v137 offset0:132 offset1:140
	ds_read2_b32 v[158:159], v137 offset0:165 offset1:173
	ds_read2_b32 v[160:161], v137 offset0:198 offset1:206
	ds_read2_b32 v[162:163], v137 offset0:231 offset1:239
	s_add_i32 s69, s69, 32
	v_add_u32_e32 v67, s69, v1
	v_mad_i64_i32 v[164:165], s[72:73], v67, s84, 0
	v_lshl_add_u64 v[164:165], v[164:165], 1, s[20:21]
	v_lshl_add_u64 v[164:165], v[164:165], 0, s[70:71]
	s_waitcnt lgkmcnt(6)
	v_cvt_pk_bf16_f32 v146, v150, v68
	s_waitcnt lgkmcnt(4)
	v_cvt_pk_bf16_f32 v147, v152, v154
	s_waitcnt lgkmcnt(2)
	v_cvt_pk_bf16_f32 v148, v156, v158
	s_waitcnt lgkmcnt(0)
	v_cvt_pk_bf16_f32 v149, v160, v162
	v_lshl_add_u64 v[164:165], v[164:165], 0, v[140:141]
	v_add_u32_e32 v67, s69, v142
	global_store_dwordx4 v[164:165], v[146:149], off nt
	s_nop 1
	v_cvt_pk_bf16_f32 v146, v151, v69
	v_mad_i64_i32 v[68:69], s[72:73], v67, s84, 0
	v_lshl_add_u64 v[68:69], v[68:69], 1, s[20:21]
	v_cvt_pk_bf16_f32 v147, v153, v155
	v_cvt_pk_bf16_f32 v148, v157, v159
	v_cvt_pk_bf16_f32 v149, v161, v163
	v_lshl_add_u64 v[68:69], v[68:69], 0, s[70:71]
	ds_read2_b32 v[150:151], v137 offset0:16 offset1:24
	ds_read2_b32 v[152:153], v137 offset0:49 offset1:57
	ds_read2_b32 v[154:155], v137 offset0:82 offset1:90
	ds_read2_b32 v[156:157], v137 offset0:115 offset1:123
	ds_read2_b32 v[158:159], v137 offset0:148 offset1:156
	ds_read2_b32 v[160:161], v137 offset0:181 offset1:189
	ds_read2_b32 v[162:163], v137 offset0:214 offset1:222
	ds_read2_b32 v[164:165], v137 offset0:247 offset1:255
	v_lshl_add_u64 v[68:69], v[68:69], 0, v[140:141]
	v_add_u32_e32 v67, s69, v143
	global_store_dwordx4 v[68:69], v[146:149], off nt
	v_mad_i64_i32 v[68:69], s[72:73], v67, s84, 0
	v_lshl_add_u64 v[68:69], v[68:69], 1, s[20:21]
	v_lshl_add_u64 v[68:69], v[68:69], 0, s[70:71]
	s_waitcnt lgkmcnt(6)
	v_cvt_pk_bf16_f32 v146, v150, v152
	s_waitcnt lgkmcnt(4)
	v_cvt_pk_bf16_f32 v147, v154, v156
	s_waitcnt lgkmcnt(2)
	v_cvt_pk_bf16_f32 v148, v158, v160
	s_waitcnt lgkmcnt(0)
	v_cvt_pk_bf16_f32 v149, v162, v164
	v_lshl_add_u64 v[68:69], v[68:69], 0, v[140:141]
	v_add_u32_e32 v67, s69, v144
	global_store_dwordx4 v[68:69], v[146:149], off nt
	v_mad_i64_i32 v[68:69], s[72:73], v67, s84, 0
	v_lshl_add_u64 v[68:69], v[68:69], 1, s[20:21]
	v_lshl_add_u64 v[68:69], v[68:69], 0, s[70:71]
	v_cvt_pk_bf16_f32 v146, v151, v153
	v_cvt_pk_bf16_f32 v147, v155, v157
	v_cvt_pk_bf16_f32 v148, v159, v161
	v_cvt_pk_bf16_f32 v149, v163, v165
	v_lshl_add_u64 v[68:69], v[68:69], 0, v[140:141]
	global_store_dwordx4 v[68:69], v[146:149], off nt
	s_waitcnt lgkmcnt(0)
	s_cbranch_vccnz .LBB0_91
	v_mov_b64_e32 v[62:63], v[130:131]
	v_mov_b64_e32 v[50:51], v[126:127]
	v_mov_b64_e32 v[58:59], v[122:123]
	v_mov_b64_e32 v[54:55], v[118:119]
	v_mov_b64_e32 v[46:47], v[114:115]
	v_mov_b64_e32 v[34:35], v[110:111]
	v_mov_b64_e32 v[42:43], v[106:107]
	v_mov_b64_e32 v[38:39], v[102:103]
	v_mov_b64_e32 v[30:31], v[98:99]
	v_mov_b64_e32 v[18:19], v[94:95]
	v_mov_b64_e32 v[26:27], v[90:91]
	v_mov_b64_e32 v[22:23], v[86:87]
	v_mov_b64_e32 v[14:15], v[82:83]
	v_mov_b64_e32 v[2:3], v[78:79]
	v_mov_b64_e32 v[10:11], v[70:71]
	v_mov_b64_e32 v[6:7], v[74:75]
	v_mov_b64_e32 v[64:65], v[132:133]
	v_mov_b64_e32 v[52:53], v[128:129]
	v_mov_b64_e32 v[60:61], v[124:125]
	v_mov_b64_e32 v[56:57], v[120:121]
	v_mov_b64_e32 v[48:49], v[116:117]
	v_mov_b64_e32 v[36:37], v[112:113]
	v_mov_b64_e32 v[44:45], v[108:109]
	v_mov_b64_e32 v[40:41], v[104:105]
	v_mov_b64_e32 v[32:33], v[100:101]
	v_mov_b64_e32 v[20:21], v[96:97]
	v_mov_b64_e32 v[28:29], v[92:93]
	v_mov_b64_e32 v[24:25], v[88:89]
	v_mov_b64_e32 v[16:17], v[84:85]
	v_mov_b64_e32 v[4:5], v[80:81]
	v_mov_b64_e32 v[12:13], v[72:73]
	v_mov_b64_e32 v[8:9], v[76:77]
	s_mov_b32 s83, s89
	s_mov_b32 s85, s90
	s_mov_b32 s84, s88
	s_mov_b64 s[20:21], s[66:67]
	s_mov_b32 s82, s91
	s_mov_b32 s81, s52
	s_branch .LBB0_91

.LBB0_1338:
	v_mov_b32_e32 v54, v191
	s_lshl_b32 s97, s4, 8
	s_add_i32 s97, s97, s79
	v_and_b32_e32 v48, 31, v54
	v_or_b32_e32 v0, s97, v48
	v_ashrrev_i32_e32 v50, 3, v54
	v_and_b32_e32 v56, 7, v54
	v_bfe_u32 v49, v54, 5, 1
	v_add_u32_e32 v0, s91, v0
	s_movk_i32 s0, 0xc00
	v_ashrrev_i32_e32 v51, 4, v54
	v_and_b32_e32 v55, 15, v54
	v_add_u32_e32 v9, s91, v50
	v_lshlrev_b32_e32 v52, 3, v56
	v_and_b32_e32 v172, 7, v51
	v_lshlrev_b32_e32 v172, 3, v172
	v_xor_b32_e32 v52, v172, v52
	v_ashrrev_i32_e32 v1, 31, v0
	v_mad_i64_i32 v[2:3], s[0:1], v0, s0, v[182:183]
	v_lshlrev_b32_e32 v180, 4, v49
	v_add_lshl_u32 v8, v51, s91, 10
	v_lshlrev_b32_e32 v53, 3, v55
	v_and_b32_e32 v172, 15, v51
	v_lshlrev_b32_e32 v172, 3, v172
	v_xor_b32_e32 v53, v172, v53
	v_lshl_or_b32 v10, v9, 6, v52
	v_add_lshl_u32 v9, v50, s92, 15
	v_lshl_add_u64 v[24:25], v[2:3], 0, v[180:181]
	v_lshlrev_b64 v[0:1], 7, v[0:1]
	v_or3_b32 v8, v8, v53, s92
	v_or3_b32 v12, v9, s91, v52
	v_add_lshl_u32 v234, v50, s92, 11
	v_add_u32_e32 v12, v12, v234
	v_mov_b32_e32 v9, v181
	global_load_dwordx4 v[96:99], v[24:25], off nt
	global_load_dwordx4 v[100:103], v[24:25], off offset:32 nt
	global_load_dwordx4 v[104:107], v[24:25], off offset:64 nt
	global_load_dwordx4 v[108:111], v[24:25], off offset:96 nt
	global_load_dwordx4 v[112:115], v[24:25], off offset:128 nt
	global_load_dwordx4 v[116:119], v[24:25], off offset:160 nt
	global_load_dwordx4 v[120:123], v[24:25], off offset:192 nt
	global_load_dwordx4 v[124:127], v[24:25], off offset:224 nt
	v_lshl_add_u64 v[2:3], s[62:63], 0, v[0:1]
	v_lshlrev_b32_e32 v4, 5, v49
	v_mov_b32_e32 v5, v181
	v_lshl_add_u64 v[14:15], v[8:9], 1, s[64:65]
	v_add_u32_e32 v8, 0x8000, v8
	v_lshl_add_u64 v[28:29], v[2:3], 0, v[4:5]
	v_lshl_add_u64 v[0:1], s[66:67], 0, v[0:1]
	v_lshl_add_u64 v[8:9], v[8:9], 1, s[64:65]
	v_mov_b32_e32 v11, v181
	v_lshl_add_u64 v[44:45], v[0:1], 0, v[4:5]
	global_load_dwordx4 v[0:3], v[28:29], off offset:16
	global_load_dwordx4 v[4:7], v[28:29], off
	s_and_b32 s5, s97, 0xe0
	s_lshl_b32 s5, s5, 5
	s_mov_b32 m0, s5
	s_nop 0
	global_load_lds_dwordx4 v[14:15], off
	s_add_i32 m0, s5, 0x2000
	s_nop 0
	global_load_lds_dwordx4 v[8:9], off
	v_lshl_add_u64 v[8:9], v[10:11], 1, s[60:61]
	v_mov_b32_e32 v13, v181
	v_lshl_add_u64 v[10:11], v[12:13], 1, s[68:69]
	s_add_i32 m0, s5, 0x8000
	s_nop 0
	global_load_lds_dwordx4 v[8:9], off
	s_add_i32 m0, s5, 0xc000
	s_nop 0
	global_load_lds_dwordx4 v[10:11], off
	v_add_u32_e32 v8, 0x220000, v12
	v_mov_b32_e32 v9, v181
	v_lshl_add_u64 v[8:9], v[8:9], 1, s[68:69]
	s_add_i32 m0, s5, 0xe000
	s_nop 0
	global_load_lds_dwordx4 v[8:9], off
	s_nop 0
	global_load_dwordx4 v[8:11], v[44:45], off offset:16
	global_load_dwordx4 v[20:23], v[44:45], off
	global_load_dwordx4 v[12:15], v[24:25], off offset:256 nt
	global_load_dwordx4 v[32:35], v[24:25], off offset:288 nt
	global_load_dwordx4 v[16:19], v[24:25], off offset:320 nt
	global_load_dwordx4 v[36:39], v[24:25], off offset:352 nt
	s_nop 0
	global_load_dwordx4 v[24:27], v[28:29], off offset:80
	global_load_dwordx4 v[40:43], v[28:29], off offset:64
	s_nop 0
	global_load_dwordx4 v[28:31], v[44:45], off offset:80
	s_nop 0
	global_load_dwordx4 v[44:47], v[44:45], off offset:64
	v_lshlrev_b32_e32 v57, 3, v54
	v_mul_lo_u32 v58, v51, s82
	v_lshlrev_b32_e32 v54, 4, v56
	v_mul_lo_u32 v56, v50, s83
	v_lshl_add_u32 v194, v55, 4, v58
	v_and_b32_e32 v55, 0x60, v54
	v_and_b32_e32 v57, 8, v57
	v_mad_u64_u32 v[184:185], s[0:1], v50, s82, v[54:55]
	v_add_u32_e32 v54, 0, v56
	v_add3_u32 v185, v54, v57, v55
	v_add_u32_e32 v56, 0, v194
	v_add_u32_e32 v54, 0xc800, v185
	v_add_u32_e32 v58, 0, v184
	v_add_u32_e32 v55, 0xe800, v185
	s_cmp_lt_i32 s4, 0
	s_mov_b32 s52, 0
	s_waitcnt vmcnt(0)
	v_mad_u32_u24 v54, v48, s83, 0
	v_add_u32_e32 v195, v54, v180
	v_and_b32_e32 v172, 0x13, v48
	v_and_b32_e32 v175, 4, v48
	v_lshl_or_b32 v172, v175, 1, v172
	v_and_b32_e32 v175, 8, v48
	v_lshrrev_b32_e32 v175, 1, v175
	v_or_b32_e32 v172, v172, v175
	v_and_b32_e32 v175, 15, v172
	v_xor_b32_e32 v175, v175, v49
	v_lshlrev_b32_e32 v175, 4, v175
	v_lshl_or_b32 v128, v172, 8, v175
	v_xor_b32_e32 v129, 0x20, v128
	v_xor_b32_e32 v130, 0x40, v128
	v_xor_b32_e32 v131, 0x60, v128
	v_xor_b32_e32 v132, 0x80, v128
	v_xor_b32_e32 v133, 0xa0, v128
	v_xor_b32_e32 v134, 0xc0, v128
	v_xor_b32_e32 v135, 0xe0, v128
	v_bfe_u32 v175, v172, 1, 3
	v_xor_b32_e32 v175, v175, v49
	v_lshlrev_b32_e32 v175, 4, v175
	v_lshl_or_b32 v136, v172, 7, v175
	v_add_u32_e32 v136, 0x8000, v136
	v_xor_b32_e32 v137, 0x20, v136
	v_xor_b32_e32 v138, 0x40, v136
	v_xor_b32_e32 v139, 0x60, v136
	v_bfe_u32 v175, v48, 1, 3
	v_xor_b32_e32 v175, v175, v49
	v_lshlrev_b32_e32 v175, 4, v175
	v_lshl_or_b32 v140, v48, 7, v175
	v_add_u32_e32 v140, 0xc000, v140
	v_xor_b32_e32 v141, 32, v140
	v_xor_b32_e32 v144, 64, v140
	v_xor_b32_e32 v145, 64, v141
	s_waitcnt lgkmcnt(0)
	s_barrier
	s_cbranch_scc1 .LBB0_1331
	v_lshlrev_b32_e32 v55, 8, v48
	v_add3_u32 v196, v54, v55, v180
	v_and_b32_e32 v55, 0xffff0000, v36
	v_lshlrev_b32_e32 v54, 16, v36
	v_and_b32_e32 v57, 0xffff0000, v32
	v_lshlrev_b32_e32 v56, 16, v32
	v_pk_mul_f32 v[58:59], v[44:45], v[56:57]
	v_pk_mul_f32 v[44:45], v[44:45], v[54:55]
	v_pk_fma_f32 v[58:59], v[40:41], v[54:55], v[58:59]
	v_pk_fma_f32 v[40:41], v[40:41], v[56:57], v[44:45] neg_lo:[0,0,1] neg_hi:[0,0,1]
	v_lshlrev_b32_e32 v36, 16, v33
	v_cvt_pk_bf16_f32 v152, v40, v41
	v_and_b32_e32 v41, 0xffff0000, v37
	v_lshlrev_b32_e32 v40, 16, v37
	v_and_b32_e32 v37, 0xffff0000, v33
	v_pk_mul_f32 v[32:33], v[46:47], v[36:37]
	s_lshl_b32 s53, s4, 2
	v_pk_fma_f32 v[32:33], v[42:43], v[40:41], v[32:33]
	v_mov_b32_e32 v200, 0
	v_cvt_pk_bf16_f32 v149, v32, v33
	v_pk_mul_f32 v[32:33], v[46:47], v[40:41]
	s_add_i32 s53, s53, 4
	v_pk_fma_f32 v[32:33], v[42:43], v[36:37], v[32:33] neg_lo:[0,0,1] neg_hi:[0,0,1]
	v_and_b32_e32 v37, 0xffff0000, v34
	v_cvt_pk_bf16_f32 v153, v32, v33
	v_and_b32_e32 v33, 0xffff0000, v38
	v_lshlrev_b32_e32 v32, 16, v38
	v_lshlrev_b32_e32 v36, 16, v34
	v_pk_mul_f32 v[40:41], v[28:29], v[36:37]
	v_pk_mul_f32 v[28:29], v[28:29], v[32:33]
	v_pk_fma_f32 v[40:41], v[24:25], v[32:33], v[40:41]
	v_pk_fma_f32 v[24:25], v[24:25], v[36:37], v[28:29] neg_lo:[0,0,1] neg_hi:[0,0,1]
	v_and_b32_e32 v29, 0xffff0000, v35
	v_lshlrev_b32_e32 v28, 16, v35
	v_cvt_pk_bf16_f32 v154, v24, v25
	v_and_b32_e32 v25, 0xffff0000, v39
	v_lshlrev_b32_e32 v24, 16, v39
	v_pk_mul_f32 v[32:33], v[30:31], v[28:29]
	v_cvt_pk_bf16_f32 v148, v58, v59
	v_pk_fma_f32 v[32:33], v[26:27], v[24:25], v[32:33]
	v_pk_mul_f32 v[24:25], v[30:31], v[24:25]
	v_cvt_pk_bf16_f32 v150, v40, v41
	v_pk_fma_f32 v[24:25], v[26:27], v[28:29], v[24:25] neg_lo:[0,0,1] neg_hi:[0,0,1]
	v_and_b32_e32 v27, 0xffff0000, v12
	v_cvt_pk_bf16_f32 v155, v24, v25
	v_and_b32_e32 v25, 0xffff0000, v16
	v_lshlrev_b32_e32 v24, 16, v16
	v_lshlrev_b32_e32 v26, 16, v12
	v_pk_mul_f32 v[28:29], v[20:21], v[26:27]
	v_pk_mul_f32 v[20:21], v[20:21], v[24:25]
	v_pk_fma_f32 v[28:29], v[4:5], v[24:25], v[28:29]
	v_pk_fma_f32 v[4:5], v[4:5], v[26:27], v[20:21] neg_lo:[0,0,1] neg_hi:[0,0,1]
	v_lshlrev_b32_e32 v16, 16, v13
	v_cvt_pk_bf16_f32 v160, v4, v5
	v_and_b32_e32 v5, 0xffff0000, v17
	v_lshlrev_b32_e32 v4, 16, v17
	v_and_b32_e32 v17, 0xffff0000, v13
	v_pk_mul_f32 v[12:13], v[22:23], v[16:17]
	v_cvt_pk_bf16_f32 v151, v32, v33
	v_pk_fma_f32 v[12:13], v[6:7], v[4:5], v[12:13]
	v_pk_mul_f32 v[4:5], v[22:23], v[4:5]
	v_cvt_pk_bf16_f32 v157, v12, v13
	v_pk_fma_f32 v[4:5], v[6:7], v[16:17], v[4:5] neg_lo:[0,0,1] neg_hi:[0,0,1]
	v_and_b32_e32 v7, 0xffff0000, v14
	v_lshlrev_b32_e32 v6, 16, v14
	v_cvt_pk_bf16_f32 v161, v4, v5
	v_and_b32_e32 v5, 0xffff0000, v18
	v_lshlrev_b32_e32 v4, 16, v18
	v_pk_mul_f32 v[12:13], v[8:9], v[6:7]
	v_cvt_pk_bf16_f32 v156, v28, v29
	v_pk_fma_f32 v[12:13], v[0:1], v[4:5], v[12:13]
	v_pk_mul_f32 v[4:5], v[8:9], v[4:5]
	v_cvt_pk_bf16_f32 v158, v12, v13
	v_pk_fma_f32 v[0:1], v[0:1], v[6:7], v[4:5] neg_lo:[0,0,1] neg_hi:[0,0,1]
	v_and_b32_e32 v5, 0xffff0000, v15
	v_lshlrev_b32_e32 v4, 16, v15
	v_cvt_pk_bf16_f32 v162, v0, v1
	v_and_b32_e32 v1, 0xffff0000, v19
	v_lshlrev_b32_e32 v0, 16, v19
	v_pk_mul_f32 v[6:7], v[10:11], v[4:5]
	v_mov_b32_e32 v199, 0xf149f2ca
	v_pk_fma_f32 v[6:7], v[2:3], v[0:1], v[6:7]
	v_pk_mul_f32 v[0:1], v[10:11], v[0:1]
	v_cvt_pk_bf16_f32 v159, v6, v7
	v_pk_fma_f32 v[0:1], v[2:3], v[4:5], v[0:1] neg_lo:[0,0,1] neg_hi:[0,0,1]
	s_mov_b32 s33, 63
	v_cvt_pk_bf16_f32 v163, v0, v1
	v_lshlrev_b32_e32 v1, 10, v51
	v_lshlrev_b32_e32 v0, 3, v49
	v_add3_u32 v186, s93, v1, v53
	v_add_u32_e32 v1, s97, v48
	v_sub_u32_e32 v197, v1, v0
	v_lshlrev_b32_e32 v0, 6, v50
	v_add3_u32 v188, s94, v0, v52
	v_lshlrev_b32_e32 v0, 15, v50
	v_add3_u32 v198, s95, v0, v52
	v_add_lshl_u32 v234, v50, s92, 11
	v_add_u32_e32 v198, v198, v234
	v_mov_b32_e32 v64, 0
	v_mov_b32_e32 v65, 0
	v_mov_b32_e32 v66, 0
	v_mov_b32_e32 v67, 0
	v_mov_b32_e32 v68, 0
	v_mov_b32_e32 v69, 0
	v_mov_b32_e32 v70, 0
	v_mov_b32_e32 v71, 0
	s_mov_b32 s0, 0
	v_mov_b32_e32 v0, 0
	v_mov_b32_e32 v1, v200
	v_mov_b32_e32 v2, v200
	v_mov_b32_e32 v3, v200
	v_mov_b32_e32 v4, v200
	v_mov_b32_e32 v5, v200
	v_mov_b32_e32 v6, v200
	v_mov_b32_e32 v7, v200
	v_mov_b32_e32 v8, v200
	v_mov_b32_e32 v9, v200
	v_mov_b32_e32 v10, v200
	v_mov_b32_e32 v11, v200
	v_mov_b32_e32 v12, v200
	v_mov_b32_e32 v13, v200
	v_mov_b32_e32 v14, v200
	v_mov_b32_e32 v15, v200
	v_mov_b32_e32 v16, 0
	v_mov_b32_e32 v17, v200
	v_mov_b32_e32 v18, v200
	v_mov_b32_e32 v19, v200
	v_mov_b32_e32 v20, v200
	v_mov_b32_e32 v21, v200
	v_mov_b32_e32 v22, v200
	v_mov_b32_e32 v23, v200
	v_mov_b32_e32 v24, v200
	v_mov_b32_e32 v25, v200
	v_mov_b32_e32 v26, v200
	v_mov_b32_e32 v27, v200
	v_mov_b32_e32 v28, v200
	v_mov_b32_e32 v29, v200
	v_mov_b32_e32 v30, v200
	v_mov_b32_e32 v31, v200
	v_mov_b32_e32 v32, 0
	v_mov_b32_e32 v33, v200
	v_mov_b32_e32 v34, v200
	v_mov_b32_e32 v35, v200
	v_mov_b32_e32 v36, v200
	v_mov_b32_e32 v37, v200
	v_mov_b32_e32 v38, v200
	v_mov_b32_e32 v39, v200
	v_mov_b32_e32 v40, v200
	v_mov_b32_e32 v41, v200
	v_mov_b32_e32 v42, v200
	v_mov_b32_e32 v43, v200
	v_mov_b32_e32 v44, v200
	v_mov_b32_e32 v45, v200
	v_mov_b32_e32 v46, v200
	v_mov_b32_e32 v47, v200
	v_mov_b32_e32 v48, 0
	v_mov_b32_e32 v49, v200
	v_mov_b32_e32 v50, v200
	v_mov_b32_e32 v51, v200
	v_mov_b32_e32 v52, v200
	v_mov_b32_e32 v53, v200
	v_mov_b32_e32 v54, v200
	v_mov_b32_e32 v55, v200
	v_mov_b32_e32 v56, v200
	v_mov_b32_e32 v57, v200
	v_mov_b32_e32 v58, v200
	v_mov_b32_e32 v59, v200
	v_mov_b32_e32 v60, v200
	v_mov_b32_e32 v61, v200
	v_mov_b32_e32 v62, v200
	v_mov_b32_e32 v63, v200
	s_mov_b32 s55, 0
	s_mov_b32 s54, 0xff7fffff
	s_mov_b32 s26, 0xff7fffff
	v_mov_b32_e32 v230, 0
	v_mov_b32_e32 v231, v230
	v_mov_b32_e32 v232, v230
	v_mov_b32_e32 v233, v230
	v_mov_b32_e32 v234, v230
	v_mov_b32_e32 v235, v230
	v_mov_b32_e32 v236, v230
	v_mov_b32_e32 v237, v230
	v_mov_b32_e32 v238, v230
	v_mov_b32_e32 v239, v230
	v_mov_b32_e32 v240, v230
	v_mov_b32_e32 v241, v230
	v_mov_b32_e32 v242, v230
	v_mov_b32_e32 v243, v230
	v_mov_b32_e32 v244, v230
	v_mov_b32_e32 v245, v230
	s_and_b32 s52, s97, 0xe0
	s_lshl_b32 s52, s52, 5
	v_xor_b32_e32 v246, 32, v193
	v_lshlrev_b32_e32 v246, 2, v246
	v_mov_b32_e32 v64, 0xff61b1e6
	v_mov_b32_e32 v65, v64
	v_mov_b32_e32 v66, v64
	v_mov_b32_e32 v67, v64
	v_mov_b32_e32 v68, v64
	v_mov_b32_e32 v69, v64
	v_mov_b32_e32 v70, v64
	v_mov_b32_e32 v71, v64
	v_mov_b32_e32 v72, v64
	v_mov_b32_e32 v73, v64
	v_mov_b32_e32 v74, v64
	v_mov_b32_e32 v75, v64
	v_mov_b32_e32 v76, v64
	v_mov_b32_e32 v77, v64
	v_mov_b32_e32 v78, v64
	v_mov_b32_e32 v79, v64
	v_add_u32_e32 v201, 0xfffe8000, v186
	v_lshlrev_b32_e32 v201, 1, v201
	v_add_u32_e32 v187, 0x10000, v201
	v_add_u32_e32 v189, 0xfffff000, v188
	v_lshlrev_b32_e32 v189, 1, v189
	v_lshlrev_b32_e32 v194, 1, v198
	v_add_u32_e32 v195, 0x440000, v194
	s_mov_b64 s[20:21], s[64:65]
	s_mov_b64 s[22:23], s[60:61]
	s_mov_b64 s[24:25], s[68:69]
